# layer-0 out-proj: residual-stream bf16 stores issued write-through (sc1) so the layer-boundary barrier's L2 write-back has less to flush
# speedup vs baseline: 1.0026x; 1.0026x over previous
.Lof0_h:
	v_lshrrev_b32_e32 v112, 6, v250
	v_mul_u32_u24_e32 v112, 0x1200, v112
	v_lshrrev_b32_e32 v113, 3, v225
	v_mul_u32_u24_e32 v113, 0x90, v113
	v_and_b32_e32 v114, 7, v225
	v_lshl_add_u32 v113, v114, 4, v113
	v_add_u32_e32 v112, v112, v113
	v_add_u32_e32 v112, 0x1000, v112
	ds_read_b128 v[96:99], v112
	ds_read_b128 v[100:103], v112 offset:1152
	ds_read_b128 v[104:107], v112 offset:2304
	ds_read_b128 v[108:111], v112 offset:3456
	s_waitcnt lgkmcnt(3)
	global_store_dwordx4 v169, v[96:99], s[100:101] sc1
	s_add_u32 s100, s100, 0x4000
	s_addc_u32 s101, s101, 0
	s_waitcnt lgkmcnt(2)
	global_store_dwordx4 v169, v[100:103], s[100:101] sc1
	s_add_u32 s100, s100, 0x4000
	s_addc_u32 s101, s101, 0
	s_waitcnt lgkmcnt(1)
	global_store_dwordx4 v169, v[104:107], s[100:101] sc1
	s_add_u32 s100, s100, 0x4000
	s_addc_u32 s101, s101, 0
	s_waitcnt lgkmcnt(0)
	global_store_dwordx4 v169, v[108:111], s[100:101] sc1
	s_add_u32 s100, s100, 0x4000
	s_addc_u32 s101, s101, 0

.Lof1_h:
	v_lshrrev_b32_e32 v80, 6, v250
	v_mul_u32_u24_e32 v80, 0x1200, v80
	v_lshrrev_b32_e32 v81, 3, v225
	v_mul_u32_u24_e32 v81, 0x90, v81
	v_and_b32_e32 v82, 7, v225
	v_lshl_add_u32 v81, v82, 4, v81
	v_add_u32_e32 v80, v80, v81
	v_add_u32_e32 v80, 0x1000, v80
	ds_read_b128 v[64:67], v80
	ds_read_b128 v[68:71], v80 offset:1152
	ds_read_b128 v[72:75], v80 offset:2304
	ds_read_b128 v[76:79], v80 offset:3456
	s_waitcnt lgkmcnt(3)
	global_store_dwordx4 v169, v[64:67], s[100:101] sc1
	s_add_u32 s100, s100, 0x4000
	s_addc_u32 s101, s101, 0
	s_waitcnt lgkmcnt(2)
	global_store_dwordx4 v169, v[68:71], s[100:101] sc1
	s_add_u32 s100, s100, 0x4000
	s_addc_u32 s101, s101, 0
	s_waitcnt lgkmcnt(1)
	global_store_dwordx4 v169, v[72:75], s[100:101] sc1
	s_add_u32 s100, s100, 0x4000
	s_addc_u32 s101, s101, 0
	s_waitcnt lgkmcnt(0)
	global_store_dwordx4 v169, v[76:79], s[100:101] sc1
	s_add_u32 s100, s100, 0x4000
	s_addc_u32 s101, s101, 0

.Lof2_h:
	v_lshrrev_b32_e32 v48, 6, v250
	v_mul_u32_u24_e32 v48, 0x1200, v48
	v_lshrrev_b32_e32 v49, 3, v225
	v_mul_u32_u24_e32 v49, 0x90, v49
	v_and_b32_e32 v50, 7, v225
	v_lshl_add_u32 v49, v50, 4, v49
	v_add_u32_e32 v48, v48, v49
	v_add_u32_e32 v48, 0x1000, v48
	ds_read_b128 v[32:35], v48
	ds_read_b128 v[36:39], v48 offset:1152
	ds_read_b128 v[40:43], v48 offset:2304
	ds_read_b128 v[44:47], v48 offset:3456
	s_waitcnt lgkmcnt(3)
	global_store_dwordx4 v169, v[32:35], s[100:101] sc1
	s_add_u32 s100, s100, 0x4000
	s_addc_u32 s101, s101, 0
	s_waitcnt lgkmcnt(2)
	global_store_dwordx4 v169, v[36:39], s[100:101] sc1
	s_add_u32 s100, s100, 0x4000
	s_addc_u32 s101, s101, 0
	s_waitcnt lgkmcnt(1)
	global_store_dwordx4 v169, v[40:43], s[100:101] sc1
	s_add_u32 s100, s100, 0x4000
	s_addc_u32 s101, s101, 0
	s_waitcnt lgkmcnt(0)
	global_store_dwordx4 v169, v[44:47], s[100:101] sc1
	s_add_u32 s100, s100, 0x4000
	s_addc_u32 s101, s101, 0

.Lof3_h:
	v_lshrrev_b32_e32 v16, 6, v250
	v_mul_u32_u24_e32 v16, 0x1200, v16
	v_lshrrev_b32_e32 v17, 3, v225
	v_mul_u32_u24_e32 v17, 0x90, v17
	v_and_b32_e32 v18, 7, v225
	v_lshl_add_u32 v17, v18, 4, v17
	v_add_u32_e32 v16, v16, v17
	v_add_u32_e32 v16, 0x1000, v16
	ds_read_b128 v[0:3], v16
	ds_read_b128 v[4:7], v16 offset:1152
	ds_read_b128 v[8:11], v16 offset:2304
	ds_read_b128 v[12:15], v16 offset:3456
	s_waitcnt lgkmcnt(3)
	global_store_dwordx4 v169, v[0:3], s[100:101] sc1
	s_add_u32 s100, s100, 0x4000
	s_addc_u32 s101, s101, 0
	s_waitcnt lgkmcnt(2)
	global_store_dwordx4 v169, v[4:7], s[100:101] sc1
	s_add_u32 s100, s100, 0x4000
	s_addc_u32 s101, s101, 0
	s_waitcnt lgkmcnt(1)
	global_store_dwordx4 v169, v[8:11], s[100:101] sc1
	s_add_u32 s100, s100, 0x4000
	s_addc_u32 s101, s101, 0
	s_waitcnt lgkmcnt(0)
	global_store_dwordx4 v169, v[12:15], s[100:101] sc1
	s_add_u32 s100, s100, 0x4000
	s_addc_u32 s101, s101, 0
